# scan phases: score fragment LDS reads issued ahead of the next-chunk global-load issue section
# baseline (speedup 1.0000x reference)
.LBB0_459:
	s_or_b64 exec, exec, s[34:35]
	v_cvt_pk_bf16_f32 v36, v12, v13
	v_cvt_pk_bf16_f32 v37, v14, v15
	v_cvt_pk_bf16_f32 v44, v32, v33
	v_cvt_pk_bf16_f32 v45, v34, v35
	v_cvt_pk_bf16_f32 v38, v16, v17
	v_cvt_pk_bf16_f32 v39, v18, v19
	ds_write2_b64 v200, v[36:37], v[44:45] offset1:4
	v_cvt_pk_bf16_f32 v36, v28, v29
	v_cvt_pk_bf16_f32 v37, v30, v31
	v_add_u32_e32 v209, 0x2000, v200
	v_cvt_pk_bf16_f32 v40, v8, v9
	v_cvt_pk_bf16_f32 v41, v10, v11
	ds_write2_b64 v209, v[38:39], v[36:37] offset0:32 offset1:36
	v_cvt_pk_bf16_f32 v36, v24, v25
	v_cvt_pk_bf16_f32 v37, v26, v27
	v_add_u32_e32 v210, 0x4000, v200
	v_cvt_pk_bf16_f32 v42, v4, v5
	v_cvt_pk_bf16_f32 v43, v6, v7
	ds_write2_b64 v210, v[40:41], v[36:37] offset0:64 offset1:68
	v_cvt_pk_bf16_f32 v36, v20, v21
	v_cvt_pk_bf16_f32 v37, v22, v23
	v_add_u32_e32 v211, 0x6000, v200
	s_add_i32 s55, s56, 1
	ds_write2_b64 v211, v[42:43], v[36:37] offset0:96 offset1:100
	s_cmp_gt_u32 s56, 2
	v_cndmask_b32_e64 v36, 0, 1, s[64:65]
	s_cselect_b64 s[72:73], -1, 0
	v_cmp_ne_u32_e64 s[34:35], 1, v36
	s_andn2_b64 vcc, exec, s[64:65]
	s_lshl_b32 s57, s55, 6
	s_waitcnt lgkmcnt(0)
	s_barrier
	v_add_u32_e32 v212, v176, v177
	ds_read_b128 v[68:71], v212
	ds_read_b128 v[72:75], v212 offset:64
	ds_read_b128 v[76:79], v212 offset:128
	ds_read_b128 v[80:83], v212 offset:192
	ds_read_b128 v[84:87], v212 offset:256
	ds_read_b128 v[88:91], v212 offset:320
	ds_read_b128 v[92:95], v212 offset:384
	ds_read_b128 v[96:99], v212 offset:448
	s_cbranch_vccnz .LBB0_464
	v_add_u32_e32 v37, s57, v145
	s_mov_b64 s[36:37], -1
	s_and_b64 vcc, exec, s[72:73]
	s_cbranch_vccz .LBB0_462
	v_sub_u32_e32 v36, 0x21ff, v37
	s_mov_b64 s[36:37], 0

.LBB0_491:
	s_or_b64 exec, exec, s[36:37]
	v_mov_b32_e32 v100, 0
	v_mov_b32_e32 v102, 0
	v_mov_b32_e32 v103, 0
	v_mov_b32_e32 v104, 0
	v_mov_b32_e32 v105, 0
	s_and_saveexec_b64 s[36:37], s[10:11]
	s_cbranch_execz .LBB0_493
	ds_read_b128 v[102:105], v201 offset:34240
	ds_read_b128 v[106:109], v201 offset:34176
	ds_read_b128 v[214:217], v201 offset:34112
	ds_read_b128 v[218:221], v201 offset:34048
	ds_read_b128 v[222:225], v201 offset:33984
	ds_read_b128 v[226:229], v201 offset:33920
	ds_read_b128 v[230:233], v201 offset:33856
	ds_read_b128 v[234:237], v201 offset:33792
	s_waitcnt lgkmcnt(0)
	s_nop 0
	v_mfma_f32_16x16x32_bf16 v[234:237], v[234:237], v[68:71], 0
	v_mfma_f32_16x16x32_bf16 v[230:233], v[230:233], v[72:75], v[234:237]
	v_mfma_f32_16x16x32_bf16 v[226:229], v[226:229], v[76:79], v[230:233]
	v_mfma_f32_16x16x32_bf16 v[222:225], v[222:225], v[80:83], v[226:229]
	v_mfma_f32_16x16x32_bf16 v[218:221], v[218:221], v[84:87], v[222:225]
	v_mfma_f32_16x16x32_bf16 v[214:217], v[214:217], v[88:91], v[218:221]
	v_mfma_f32_16x16x32_bf16 v[106:109], v[106:109], v[92:95], v[214:217]
	v_mfma_f32_16x16x32_bf16 v[102:105], v[102:105], v[96:99], v[106:109]

.LBB0_3326:
	s_or_b64 exec, exec, s[4:5]
	v_cvt_pk_bf16_f32 v12, v4, v5
	v_cvt_pk_bf16_f32 v13, v6, v7
	ds_write_b64 v127, v[12:13] offset:53248
	v_cvt_pk_bf16_f32 v12, v8, v9
	v_cvt_pk_bf16_f32 v13, v10, v11
	s_add_i32 s76, s67, 1
	ds_write_b64 v127, v[12:13] offset:57600
	s_cmp_gt_u32 s67, 2
	v_cndmask_b32_e64 v12, 0, 1, s[64:65]
	s_cselect_b64 s[74:75], -1, 0
	s_lshl_b32 s68, s76, 6
	v_cmp_ne_u32_e64 s[48:49], 1, v12
	s_andn2_b64 vcc, exec, s[64:65]
	v_add_u32_e32 v14, s66, v90
	s_waitcnt lgkmcnt(0)
	s_barrier
	v_add_u32_e32 v88, v109, v110
	v_add_u32_e32 v248, v110, v45
	v_add_u32_e32 v249, v110, v117
	ds_read_b128 v[232:235], v88
	ds_read_b128 v[236:239], v88 offset:64
	ds_read_b128 v[240:243], v88 offset:128
	ds_read_b128 v[244:247], v88 offset:192
	ds_read_b128 v[182:185], v248 offset:17600
	ds_read_b128 v[80:83], v248 offset:17536
	ds_read_b128 v[84:87], v248 offset:17472
	ds_read_b128 v[138:141], v248 offset:17408
	ds_read_b128 v[166:169], v249 offset:17600
	ds_read_b128 v[170:173], v249 offset:17536
	ds_read_b128 v[174:177], v249 offset:17472
	ds_read_b128 v[178:181], v249 offset:17408
	s_cbranch_vccnz .LBB0_3331
	v_add_u32_e32 v13, s68, v90
	s_mov_b64 s[4:5], -1
	s_and_b64 vcc, exec, s[74:75]
	s_cbranch_vccz .LBB0_3329
	v_sub_u32_e32 v12, 0x21ff, v13
	s_mov_b64 s[4:5], 0

.LBB0_3382:
	s_or_b64 exec, exec, s[50:51]
	v_mov_b32_e32 v12, 0
	v_mov_b32_e32 v32, 0
	v_mov_b32_e32 v33, 0
	v_mov_b32_e32 v34, 0
	v_mov_b32_e32 v35, 0
	s_and_saveexec_b64 s[4:5], s[24:25]
	s_cbranch_execz .LBB0_3384
	s_waitcnt lgkmcnt(4)
	v_mfma_f32_16x16x32_bf16 v[138:141], v[138:141], v[232:235], 0
	v_mfma_f32_16x16x32_bf16 v[84:87], v[84:87], v[236:239], v[138:141]
	v_mfma_f32_16x16x32_bf16 v[80:83], v[80:83], v[240:243], v[84:87]
	v_mfma_f32_16x16x32_bf16 v[32:35], v[182:185], v[244:247], v[80:83]
.LBB0_3384:
	s_or_b64 exec, exec, s[4:5]
	s_nop 6
	v_cndmask_b32_e64 v13, v32, 0, s[28:29]
	v_cndmask_b32_e64 v14, 0, v33, s[30:31]
	v_cndmask_b32_e64 v13, v13, v32, s[30:31]
	v_cndmask_b32_e64 v15, v34, 0, s[34:35]
	v_cndmask_b32_e64 v32, v35, 0, s[36:37]
	v_cvt_pk_bf16_f32 v14, v13, v14
	v_cvt_pk_bf16_f32 v15, v15, v32
	ds_write_b64 v118, v[14:15] offset:44032
	v_mov_b32_e32 v13, 0
	v_mov_b32_e32 v14, 0
	v_mov_b32_e32 v15, 0
	s_and_saveexec_b64 s[4:5], s[26:27]
	s_cbranch_execz .LBB0_3386
	s_waitcnt lgkmcnt(1)
	v_mfma_f32_16x16x32_bf16 v[16:19], v[178:181], v[232:235], 0
	v_mfma_f32_16x16x32_bf16 v[16:19], v[174:177], v[236:239], v[16:19]
	v_mfma_f32_16x16x32_bf16 v[16:19], v[170:173], v[240:243], v[16:19]
	v_mfma_f32_16x16x32_bf16 v[12:15], v[166:169], v[244:247], v[16:19]
